# phase E and D epilogues: all 16 staged-row LDS reads issued up front (counted lgkmcnt waits), D epilogue loop unrolled
# baseline (speedup 1.0000x reference)
; #define MFMA16(a, b, c) __builtin_amdgcn_mfma_f32_16x16x32_bf16((a), (b), (c), 0, 0, 0)
; DI void gemm_tile(const bf16_t* __restrict__ A, int lda, const bf16_t* __restrict__ Bt, int ldb, int bvalid, int K, f32x4 (&acc)[4][4], char* lds, bool preloaded = false) {
;     ...
;   auto compute = [&](int st) {
;     const char* base = lds + st * 32768;
;     bf16x8 af[2][4], bfr[2][4];
; #pragma unroll
;     for (int s = 0; s < 2; ++s) {
;       const int ch = ((4 * s + fq) ^ fx) << 4;
; #pragma unroll
;       for (int mi = 0; mi < 4; ++mi) af[s][mi] = *(const bf16x8*)(base + (wm * 64 + mi * 16 + fr) * 128 + ch);
; #pragma unroll
;       for (int ni = 0; ni < 4; ++ni) bfr[s][ni] = *(const bf16x8*)(base + 16384 + (wn * 64 + ni * 16 + fr) * 128 + ch);
;     }
;     __builtin_amdgcn_s_setprio(1);
; #pragma unroll
;     for (int s = 0; s < 2; ++s)
; #pragma unroll
;       for (int mi = 0; mi < 4; ++mi)
; #pragma unroll
;         for (int ni = 0; ni < 4; ++ni) acc[mi][ni] = MFMA16(af[s][mi], bfr[s][ni], acc[mi][ni]);
;     __builtin_amdgcn_s_setprio(0);
;   };
;   const int nk = K >> 6;
;   if (!preloaded) { GLDS(0, 0) }
;   __syncthreads();
;   for (int kt = 0; kt < nk; ++kt) {
;     if (kt + 1 < nk) { GLDS((kt + 1) & 1, (kt + 1) << 6) }
;     compute(kt & 1);
;     __syncthreads();
;   }
.LBB0_170:
	v_lshl_add_u64 v[150:151], v[132:133], 0, s[8:9]
	s_mov_b64 s[24:25], 0x624e080
	s_add_i32 s23, s22, 0x8000
	v_lshl_add_u64 v[152:153], v[150:151], 0, s[24:25]
	s_and_b32 s24, s23, 0x8000
	v_add_u32_e32 v0, s24, v145
	v_add_u32_e32 v154, 0x4000, v0
	v_readfirstlane_b32 s24, v0
	s_mov_b32 m0, s24
	v_readfirstlane_b32 s24, v154
	global_load_lds_dwordx4 v[152:153], off
	v_lshl_add_u64 v[152:153], v[134:135], 0, s[8:9]
	s_mov_b32 m0, s24
	s_mov_b64 s[24:25], 0x625f080
	v_add_u32_e32 v154, 0x1000, v0
	global_load_lds_dwordx4 v[152:153], off
	v_lshl_add_u64 v[152:153], v[150:151], 0, s[24:25]
	v_readfirstlane_b32 s24, v154
	v_add_u32_e32 v154, 0x5000, v0
	s_mov_b32 m0, s24
	v_readfirstlane_b32 s24, v154
	global_load_lds_dwordx4 v[152:153], off
	v_lshl_add_u64 v[152:153], v[136:137], 0, s[8:9]
	s_mov_b32 m0, s24
	s_mov_b64 s[24:25], 0x6270080
	v_add_u32_e32 v154, 0x2000, v0
	global_load_lds_dwordx4 v[152:153], off
	v_lshl_add_u64 v[152:153], v[150:151], 0, s[24:25]
	v_readfirstlane_b32 s24, v154
	v_add_u32_e32 v154, 0x6000, v0
	s_mov_b32 m0, s24
	v_readfirstlane_b32 s24, v154
	global_load_lds_dwordx4 v[152:153], off
	v_lshl_add_u64 v[152:153], v[138:139], 0, s[8:9]
	s_mov_b32 m0, s24
	s_mov_b64 s[24:25], 0x6281080
	global_load_lds_dwordx4 v[152:153], off
	v_add_u32_e32 v152, 0x3000, v0
	v_lshl_add_u64 v[150:151], v[150:151], 0, s[24:25]
	v_readfirstlane_b32 s24, v152
	v_add_u32_e32 v0, 0x7000, v0
	s_mov_b32 m0, s24
	v_readfirstlane_b32 s24, v0
	global_load_lds_dwordx4 v[150:151], off
	v_lshl_add_u64 v[150:151], v[140:141], 0, s[8:9]
	s_mov_b32 m0, s24
	s_and_b32 s22, s22, 0x8000
	global_load_lds_dwordx4 v[150:151], off
	v_or_b32_e32 v0, s22, v149
	v_add_u32_e32 v179, v0, v148
	v_add_u32_e32 v0, v0, v146
	ds_read_b128 v[150:153], v179
	ds_read_b128 v[154:157], v179 offset:2048
	ds_read_b128 v[180:183], v179 offset:4096
	ds_read_b128 v[184:187], v179 offset:6144
	ds_read_b128 v[188:191], v0 offset:16384
	ds_read_b128 v[192:195], v0 offset:18432
	ds_read_b128 v[196:199], v0 offset:20480
	ds_read_b128 v[200:203], v0 offset:22528
	v_or_b32_e32 v0, s22, v147
	v_add_u32_e32 v179, v0, v148
	v_add_u32_e32 v0, v0, v146
	ds_read_b128 v[204:207], v179
	ds_read_b128 v[208:211], v179 offset:2048
	ds_read_b128 v[212:215], v179 offset:4096
	ds_read_b128 v[216:219], v179 offset:6144
	ds_read_b128 v[220:223], v0 offset:16384
	ds_read_b128 v[224:227], v0 offset:18432
	ds_read_b128 v[228:231], v0 offset:20480
	ds_read_b128 v[232:235], v0 offset:22528
	s_setprio 1
	s_waitcnt lgkmcnt(8)
	v_mfma_f32_16x16x32_bf16 v[126:129], v[150:153], v[188:191], v[126:129]
	v_mfma_f32_16x16x32_bf16 v[122:125], v[150:153], v[192:195], v[122:125]
	v_mfma_f32_16x16x32_bf16 v[118:121], v[150:153], v[196:199], v[118:121]
	v_mfma_f32_16x16x32_bf16 v[114:117], v[150:153], v[200:203], v[114:117]
	v_mfma_f32_16x16x32_bf16 v[110:113], v[154:157], v[188:191], v[110:113]
	v_mfma_f32_16x16x32_bf16 v[106:109], v[154:157], v[192:195], v[106:109]
	v_mfma_f32_16x16x32_bf16 v[102:105], v[154:157], v[196:199], v[102:105]
	v_mfma_f32_16x16x32_bf16 v[98:101], v[154:157], v[200:203], v[98:101]
	v_mfma_f32_16x16x32_bf16 v[94:97], v[180:183], v[188:191], v[94:97]
	v_mfma_f32_16x16x32_bf16 v[90:93], v[180:183], v[192:195], v[90:93]
	v_mfma_f32_16x16x32_bf16 v[86:89], v[180:183], v[196:199], v[86:89]
	v_mfma_f32_16x16x32_bf16 v[82:85], v[180:183], v[200:203], v[82:85]
	v_mfma_f32_16x16x32_bf16 v[78:81], v[184:187], v[188:191], v[78:81]
	v_mfma_f32_16x16x32_bf16 v[74:77], v[184:187], v[192:195], v[74:77]
	v_mfma_f32_16x16x32_bf16 v[70:73], v[184:187], v[196:199], v[70:73]
	v_mfma_f32_16x16x32_bf16 v[66:69], v[184:187], v[200:203], v[66:69]
	s_waitcnt lgkmcnt(0)
	v_mfma_f32_16x16x32_bf16 v[126:129], v[204:207], v[220:223], v[126:129]
	v_mfma_f32_16x16x32_bf16 v[122:125], v[204:207], v[224:227], v[122:125]
	v_mfma_f32_16x16x32_bf16 v[118:121], v[204:207], v[228:231], v[118:121]
	v_mfma_f32_16x16x32_bf16 v[114:117], v[204:207], v[232:235], v[114:117]
	v_mfma_f32_16x16x32_bf16 v[110:113], v[208:211], v[220:223], v[110:113]
	v_mfma_f32_16x16x32_bf16 v[106:109], v[208:211], v[224:227], v[106:109]
	v_mfma_f32_16x16x32_bf16 v[102:105], v[208:211], v[228:231], v[102:105]
	v_mfma_f32_16x16x32_bf16 v[98:101], v[208:211], v[232:235], v[98:101]
	v_mfma_f32_16x16x32_bf16 v[94:97], v[212:215], v[220:223], v[94:97]
	v_mfma_f32_16x16x32_bf16 v[90:93], v[212:215], v[224:227], v[90:93]
	v_mfma_f32_16x16x32_bf16 v[86:89], v[212:215], v[228:231], v[86:89]
	v_mfma_f32_16x16x32_bf16 v[82:85], v[212:215], v[232:235], v[82:85]
	v_mfma_f32_16x16x32_bf16 v[78:81], v[216:219], v[220:223], v[78:81]
	v_mfma_f32_16x16x32_bf16 v[74:77], v[216:219], v[224:227], v[74:77]
	v_mfma_f32_16x16x32_bf16 v[70:73], v[216:219], v[228:231], v[70:73]
	v_mfma_f32_16x16x32_bf16 v[66:69], v[216:219], v[232:235], v[66:69]
	s_setprio 0
	s_add_u32 s8, s8, 0x80
	s_addc_u32 s9, s9, 0
	s_cmpk_eq_i32 s8, 0x780
	s_mov_b32 s22, s23
	s_waitcnt vmcnt(0)
	s_barrier
	s_cbranch_scc0 .LBB0_170
; DI void phaseE_tile(const P& p, int layer, int mt, int nt, char* lds) {
;     ...
;   float* tile = (float*)lds;
;   stage_acc(acc, tile, wm, wn, fr, fq);
;   __syncthreads();
;   bf16_t* XB = (bf16_t*)(p.ws + W_XB);
;   float* SS = (float*)(p.ws + W_SS);
; #pragma unroll
;   for (int ps = 0; ps < 16; ++ps) {
;     const int lr = ps * 8 + wm * 4 + fq, row = row0 + lr;
;     const f32x4 v = xr[ps] + *(const f32x4*)(tile + lr * EPS + wn * 64 + fr * 4);
;     *(f32x4*)(XF + (size_t)row * DM + col) = v;
	v_add_u32_e32 v0, v149, v148
	ds_read_b128 v[132:135], v0 offset:32768
	ds_read_b128 v[136:139], v0 offset:34816
	ds_read_b128 v[150:153], v0 offset:36864
	ds_read_b128 v[154:157], v0 offset:38912
	v_add_u32_e32 v0, v149, v146
	ds_read_b128 v[180:183], v0 offset:49152
	ds_read_b128 v[184:187], v0 offset:51200
	ds_read_b128 v[188:191], v0 offset:53248
	ds_read_b128 v[192:195], v0 offset:55296
	v_add_u32_e32 v0, v147, v148
	ds_read_b128 v[196:199], v0 offset:32768
	ds_read_b128 v[200:203], v0 offset:34816
	ds_read_b128 v[204:207], v0 offset:36864
	ds_read_b128 v[208:211], v0 offset:38912
	v_add_u32_e32 v0, v147, v146
	ds_read_b128 v[146:149], v0 offset:49152
	ds_read_b128 v[212:215], v0 offset:51200
	ds_read_b128 v[216:219], v0 offset:53248
	ds_read_b128 v[220:223], v0 offset:55296
	s_setprio 1
	s_waitcnt lgkmcnt(9)
	v_mfma_f32_16x16x32_bf16 v[70:73], v[154:157], v[188:191], v[70:73]
	s_waitcnt lgkmcnt(8)
	v_mfma_f32_16x16x32_bf16 v[66:69], v[154:157], v[192:195], v[66:69]
	v_mfma_f32_16x16x32_bf16 v[126:129], v[132:135], v[180:183], v[126:129]
	v_mfma_f32_16x16x32_bf16 v[122:125], v[132:135], v[184:187], v[122:125]
	v_mfma_f32_16x16x32_bf16 v[118:121], v[132:135], v[188:191], v[118:121]
	v_mfma_f32_16x16x32_bf16 v[114:117], v[132:135], v[192:195], v[114:117]
	v_mfma_f32_16x16x32_bf16 v[110:113], v[136:139], v[180:183], v[110:113]
	v_mfma_f32_16x16x32_bf16 v[106:109], v[136:139], v[184:187], v[106:109]
	v_mfma_f32_16x16x32_bf16 v[102:105], v[136:139], v[188:191], v[102:105]
	v_mfma_f32_16x16x32_bf16 v[98:101], v[136:139], v[192:195], v[98:101]
	v_mfma_f32_16x16x32_bf16 v[94:97], v[150:153], v[180:183], v[94:97]
	v_mfma_f32_16x16x32_bf16 v[90:93], v[150:153], v[184:187], v[90:93]
	v_mfma_f32_16x16x32_bf16 v[86:89], v[150:153], v[188:191], v[86:89]
	v_mfma_f32_16x16x32_bf16 v[82:85], v[150:153], v[192:195], v[82:85]
	v_mfma_f32_16x16x32_bf16 v[78:81], v[154:157], v[180:183], v[78:81]
	v_mfma_f32_16x16x32_bf16 v[74:77], v[154:157], v[184:187], v[74:77]
	s_waitcnt lgkmcnt(1)
	v_mfma_f32_16x16x32_bf16 v[70:73], v[208:211], v[216:219], v[70:73]
	s_waitcnt lgkmcnt(0)
	v_mfma_f32_16x16x32_bf16 v[66:69], v[208:211], v[220:223], v[66:69]
	v_mfma_f32_16x16x32_bf16 v[126:129], v[196:199], v[146:149], v[126:129]
	v_mfma_f32_16x16x32_bf16 v[122:125], v[196:199], v[212:215], v[122:125]
	v_mfma_f32_16x16x32_bf16 v[118:121], v[196:199], v[216:219], v[118:121]
	v_mfma_f32_16x16x32_bf16 v[114:117], v[196:199], v[220:223], v[114:117]
	v_mfma_f32_16x16x32_bf16 v[110:113], v[200:203], v[146:149], v[110:113]
	v_mfma_f32_16x16x32_bf16 v[106:109], v[200:203], v[212:215], v[106:109]
	v_mfma_f32_16x16x32_bf16 v[102:105], v[200:203], v[216:219], v[102:105]
	v_mfma_f32_16x16x32_bf16 v[98:101], v[200:203], v[220:223], v[98:101]
	v_mfma_f32_16x16x32_bf16 v[94:97], v[204:207], v[146:149], v[94:97]
	v_mfma_f32_16x16x32_bf16 v[90:93], v[204:207], v[212:215], v[90:93]
	v_mfma_f32_16x16x32_bf16 v[86:89], v[204:207], v[216:219], v[86:89]
	v_mfma_f32_16x16x32_bf16 v[82:85], v[204:207], v[220:223], v[82:85]
	v_mfma_f32_16x16x32_bf16 v[78:81], v[208:211], v[146:149], v[78:81]
	v_mfma_f32_16x16x32_bf16 v[74:77], v[208:211], v[212:215], v[74:77]
	s_setprio 0
	v_lshlrev_b32_e32 v0, 2, v142
	v_lshl_or_b32 v132, s20, 6, v0
	v_lshl_or_b32 v0, s19, 8, v144
	v_mad_u64_u32 v[132:133], s[8:9], v132, s56, v[0:1]
	v_add_u32_e32 v0, 0x400, v132
	s_barrier
	ds_write2_b32 v132, v126, v122 offset1:16
	ds_write2_b32 v132, v127, v123 offset0:132 offset1:148
	ds_write2_b32 v0, v128, v124 offset0:8 offset1:24
	ds_write2_b32 v0, v129, v125 offset0:140 offset1:156
	ds_write2_b32 v132, v118, v114 offset0:32 offset1:48
	ds_write2_b32 v132, v119, v115 offset0:164 offset1:180
	ds_write2_b32 v0, v120, v116 offset0:40 offset1:56
	ds_write2_b32 v0, v121, v117 offset0:172 offset1:188
	v_add_u32_e32 v0, 0x2000, v132
	ds_write2_b32 v0, v110, v106 offset0:64 offset1:80
	ds_write2_b32 v0, v111, v107 offset0:196 offset1:212
	v_add_u32_e32 v106, 0x2400, v132
	ds_write2_b32 v106, v112, v108 offset0:72 offset1:88
	ds_write2_b32 v106, v113, v109 offset0:204 offset1:220
	ds_write2_b32 v0, v102, v98 offset0:96 offset1:112
	ds_write2_b32 v0, v103, v99 offset0:228 offset1:244
	ds_write2_b32 v106, v104, v100 offset0:104 offset1:120
	ds_write2_b32 v106, v105, v101 offset0:236 offset1:252
	v_add_u32_e32 v0, 0x4000, v132
	ds_write2_b32 v0, v94, v90 offset0:128 offset1:144
	v_add_u32_e32 v90, 0x4400, v132
	ds_write2_b32 v90, v95, v91 offset0:4 offset1:20
	ds_write2_b32 v90, v96, v92 offset0:136 offset1:152
	v_add_u32_e32 v91, 0x4800, v132
	ds_write2_b32 v91, v97, v93 offset0:12 offset1:28
	ds_write2_b32 v0, v86, v82 offset0:160 offset1:176
	ds_write2_b32 v90, v87, v83 offset0:36 offset1:52
	ds_write2_b32 v90, v88, v84 offset0:168 offset1:184
	ds_write2_b32 v91, v89, v85 offset0:44 offset1:60
	v_add_u32_e32 v0, 0x6000, v132
	ds_write2_b32 v0, v78, v74 offset0:192 offset1:208
	v_add_u32_e32 v74, 0x6400, v132
	ds_write2_b32 v74, v79, v75 offset0:68 offset1:84
	ds_write2_b32 v74, v80, v76 offset0:200 offset1:216
	v_add_u32_e32 v75, 0x6800, v132
	ds_write2_b32 v75, v81, v77 offset0:76 offset1:92
	ds_write2_b32 v0, v70, v66 offset0:224 offset1:240
	ds_write2_b32 v74, v71, v67 offset0:100 offset1:116
	ds_write2_b32 v74, v72, v68 offset0:232 offset1:248
	ds_write2_b32 v75, v73, v69 offset0:108 offset1:124
	v_or_b32_e32 v68, s11, v142
	v_lshlrev_b32_e32 v0, 2, v144
	v_lshl_add_u32 v0, s21, 2, v0
	v_mul_lo_u32 v66, v68, s56
	v_add_u32_e32 v0, v0, v66
	s_waitcnt lgkmcnt(0)
	s_barrier
	ds_read_b128 v[180:183], v0
	ds_read_b128 v[184:187], v0 offset:4224
	ds_read_b128 v[188:191], v0 offset:8448
	ds_read_b128 v[192:195], v0 offset:12672
	ds_read_b128 v[196:199], v0 offset:16896
	ds_read_b128 v[200:203], v0 offset:21120
	ds_read_b128 v[204:207], v0 offset:25344
	ds_read_b128 v[208:211], v0 offset:29568
	ds_read_b128 v[212:215], v0 offset:33792
	ds_read_b128 v[216:219], v0 offset:38016
	ds_read_b128 v[220:223], v0 offset:42240
	ds_read_b128 v[224:227], v0 offset:46464
	ds_read_b128 v[228:231], v0 offset:50688
	ds_read_b128 v[232:235], v0 offset:54912
	ds_read_b128 v[150:153], v0 offset:59136
	ds_read_b128 v[154:157], v0 offset:63360
	v_add_u32_e32 v70, s10, v68
	v_ashrrev_i32_e32 v71, 31, v70
	v_lshl_add_u64 v[66:67], v[130:131], 2, s[88:89]
	v_lshlrev_b64 v[68:69], 12, v[70:71]
	s_waitcnt lgkmcnt(15)
	v_pk_add_f32 v[4:5], v[4:5], v[182:183]
	v_pk_add_f32 v[2:3], v[2:3], v[180:181]
	v_lshl_add_u64 v[68:69], v[66:67], 0, v[68:69]
	s_and_b64 vcc, exec, s[38:39]
	s_mov_b64 s[8:9], -1
	global_store_dwordx4 v[68:69], v[2:5], off
	s_cbranch_vccnz .LBB0_173
	s_mov_b64 s[8:9], 0

; DI void phaseE_tile(const P& p, int layer, int mt, int nt, char* lds) {
;     ...
;   for (int ps = 0; ps < 16; ++ps) {
;     const int lr = ps * 8 + wm * 4 + fq, row = row0 + lr;
;     const f32x4 v = xr[ps] + *(const f32x4*)(tile + lr * EPS + wn * 64 + fr * 4);
;     *(f32x4*)(XF + (size_t)row * DM + col) = v;
.LBB0_177:
	s_or_b64 exec, exec, s[10:11]
	v_add_u32_e32 v72, 8, v70
	v_ashrrev_i32_e32 v73, 31, v72
	s_mov_b64 s[10:11], -1
	s_and_b64 vcc, exec, s[38:39]
	s_waitcnt lgkmcnt(14)
	v_pk_add_f32 v[2:3], v[6:7], v[184:185]
	v_lshlrev_b64 v[6:7], 12, v[72:73]
	v_pk_add_f32 v[4:5], v[8:9], v[186:187]
	v_lshl_add_u64 v[6:7], v[66:67], 0, v[6:7]
	global_store_dwordx4 v[6:7], v[2:5], off
	s_cbranch_vccnz .LBB0_179
	s_mov_b64 s[10:11], 0

; DI void phaseE_tile(const P& p, int layer, int mt, int nt, char* lds) {
;     ...
;   for (int ps = 0; ps < 16; ++ps) {
;     const int lr = ps * 8 + wm * 4 + fq, row = row0 + lr;
;     const f32x4 v = xr[ps] + *(const f32x4*)(tile + lr * EPS + wn * 64 + fr * 4);
;     *(f32x4*)(XF + (size_t)row * DM + col) = v;
.LBB0_183:
	s_or_b64 exec, exec, s[10:11]
	v_add_u32_e32 v6, 16, v70
	v_ashrrev_i32_e32 v7, 31, v6
	v_lshlrev_b64 v[8:9], 12, v[6:7]
	v_lshl_add_u64 v[8:9], v[66:67], 0, v[8:9]
	s_waitcnt lgkmcnt(13)
	v_pk_add_f32 v[4:5], v[12:13], v[190:191]
	v_pk_add_f32 v[2:3], v[10:11], v[188:189]
	s_mov_b64 s[10:11], -1
	s_and_b64 vcc, exec, s[38:39]
	global_store_dwordx4 v[8:9], v[2:5], off
	s_cbranch_vccnz .LBB0_185
	s_mov_b64 s[10:11], 0

; DI void phaseE_tile(const P& p, int layer, int mt, int nt, char* lds) {
;     ...
;   for (int ps = 0; ps < 16; ++ps) {
;     const int lr = ps * 8 + wm * 4 + fq, row = row0 + lr;
;     const f32x4 v = xr[ps] + *(const f32x4*)(tile + lr * EPS + wn * 64 + fr * 4);
;     *(f32x4*)(XF + (size_t)row * DM + col) = v;
.LBB0_189:
	s_or_b64 exec, exec, s[10:11]
	v_add_u32_e32 v6, 24, v70
	v_ashrrev_i32_e32 v7, 31, v6
	v_lshlrev_b64 v[8:9], 12, v[6:7]
	v_lshl_add_u64 v[8:9], v[66:67], 0, v[8:9]
	s_waitcnt lgkmcnt(12)
	v_pk_add_f32 v[4:5], v[16:17], v[194:195]
	v_pk_add_f32 v[2:3], v[14:15], v[192:193]
	s_mov_b64 s[10:11], -1
	s_and_b64 vcc, exec, s[38:39]
	global_store_dwordx4 v[8:9], v[2:5], off
	s_cbranch_vccnz .LBB0_191
	s_mov_b64 s[10:11], 0

; DI void phaseE_tile(const P& p, int layer, int mt, int nt, char* lds) {
;     ...
;   for (int ps = 0; ps < 16; ++ps) {
;     const int lr = ps * 8 + wm * 4 + fq, row = row0 + lr;
;     const f32x4 v = xr[ps] + *(const f32x4*)(tile + lr * EPS + wn * 64 + fr * 4);
;     *(f32x4*)(XF + (size_t)row * DM + col) = v;
.LBB0_195:
	s_or_b64 exec, exec, s[10:11]
	v_add_u32_e32 v6, 32, v70
	v_ashrrev_i32_e32 v7, 31, v6
	v_lshlrev_b64 v[8:9], 12, v[6:7]
	v_lshl_add_u64 v[8:9], v[66:67], 0, v[8:9]
	s_waitcnt lgkmcnt(11)
	v_pk_add_f32 v[4:5], v[20:21], v[198:199]
	v_pk_add_f32 v[2:3], v[18:19], v[196:197]
	s_mov_b64 s[10:11], -1
	s_and_b64 vcc, exec, s[38:39]
	global_store_dwordx4 v[8:9], v[2:5], off
	s_cbranch_vccnz .LBB0_197
	s_mov_b64 s[10:11], 0

; DI void phaseE_tile(const P& p, int layer, int mt, int nt, char* lds) {
;     ...
;   for (int ps = 0; ps < 16; ++ps) {
;     const int lr = ps * 8 + wm * 4 + fq, row = row0 + lr;
;     const f32x4 v = xr[ps] + *(const f32x4*)(tile + lr * EPS + wn * 64 + fr * 4);
;     *(f32x4*)(XF + (size_t)row * DM + col) = v;
.LBB0_201:
	s_or_b64 exec, exec, s[10:11]
	v_add_u32_e32 v6, 40, v70
	v_ashrrev_i32_e32 v7, 31, v6
	v_lshlrev_b64 v[8:9], 12, v[6:7]
	v_lshl_add_u64 v[8:9], v[66:67], 0, v[8:9]
	s_waitcnt lgkmcnt(10)
	v_pk_add_f32 v[4:5], v[24:25], v[202:203]
	v_pk_add_f32 v[2:3], v[22:23], v[200:201]
	s_mov_b64 s[10:11], -1
	s_and_b64 vcc, exec, s[38:39]
	global_store_dwordx4 v[8:9], v[2:5], off
	s_cbranch_vccnz .LBB0_203
	s_mov_b64 s[10:11], 0

; DI void phaseE_tile(const P& p, int layer, int mt, int nt, char* lds) {
;     ...
;   for (int ps = 0; ps < 16; ++ps) {
;     const int lr = ps * 8 + wm * 4 + fq, row = row0 + lr;
;     const f32x4 v = xr[ps] + *(const f32x4*)(tile + lr * EPS + wn * 64 + fr * 4);
;     *(f32x4*)(XF + (size_t)row * DM + col) = v;
.LBB0_207:
	s_or_b64 exec, exec, s[10:11]
	v_add_u32_e32 v6, 48, v70
	v_ashrrev_i32_e32 v7, 31, v6
	v_lshlrev_b64 v[8:9], 12, v[6:7]
	v_lshl_add_u64 v[8:9], v[66:67], 0, v[8:9]
	s_waitcnt lgkmcnt(9)
	v_pk_add_f32 v[4:5], v[28:29], v[206:207]
	v_pk_add_f32 v[2:3], v[26:27], v[204:205]
	s_mov_b64 s[10:11], -1
	s_and_b64 vcc, exec, s[38:39]
	global_store_dwordx4 v[8:9], v[2:5], off
	s_cbranch_vccnz .LBB0_209
	s_mov_b64 s[10:11], 0

; DI void phaseE_tile(const P& p, int layer, int mt, int nt, char* lds) {
;     ...
;   for (int ps = 0; ps < 16; ++ps) {
;     const int lr = ps * 8 + wm * 4 + fq, row = row0 + lr;
;     const f32x4 v = xr[ps] + *(const f32x4*)(tile + lr * EPS + wn * 64 + fr * 4);
;     *(f32x4*)(XF + (size_t)row * DM + col) = v;
.LBB0_213:
	s_or_b64 exec, exec, s[10:11]
	v_add_u32_e32 v6, 56, v70
	v_ashrrev_i32_e32 v7, 31, v6
	v_lshlrev_b64 v[8:9], 12, v[6:7]
	v_lshl_add_u64 v[8:9], v[66:67], 0, v[8:9]
	s_waitcnt lgkmcnt(8)
	v_pk_add_f32 v[4:5], v[32:33], v[210:211]
	v_pk_add_f32 v[2:3], v[30:31], v[208:209]
	s_mov_b64 s[10:11], -1
	s_and_b64 vcc, exec, s[38:39]
	global_store_dwordx4 v[8:9], v[2:5], off
	s_cbranch_vccnz .LBB0_215
	s_mov_b64 s[10:11], 0

; DI void phaseE_tile(const P& p, int layer, int mt, int nt, char* lds) {
;     ...
;   for (int ps = 0; ps < 16; ++ps) {
;     const int lr = ps * 8 + wm * 4 + fq, row = row0 + lr;
;     const f32x4 v = xr[ps] + *(const f32x4*)(tile + lr * EPS + wn * 64 + fr * 4);
;     *(f32x4*)(XF + (size_t)row * DM + col) = v;
.LBB0_219:
	s_or_b64 exec, exec, s[10:11]
	v_add_u32_e32 v6, 64, v70
	v_ashrrev_i32_e32 v7, 31, v6
	v_lshlrev_b64 v[8:9], 12, v[6:7]
	v_lshl_add_u64 v[8:9], v[66:67], 0, v[8:9]
	s_waitcnt lgkmcnt(7)
	v_pk_add_f32 v[4:5], v[36:37], v[214:215]
	v_pk_add_f32 v[2:3], v[34:35], v[212:213]
	s_mov_b64 s[10:11], -1
	s_and_b64 vcc, exec, s[38:39]
	global_store_dwordx4 v[8:9], v[2:5], off
	s_cbranch_vccnz .LBB0_221
	s_mov_b64 s[10:11], 0

; DI void phaseE_tile(const P& p, int layer, int mt, int nt, char* lds) {
;     ...
;   for (int ps = 0; ps < 16; ++ps) {
;     const int lr = ps * 8 + wm * 4 + fq, row = row0 + lr;
;     const f32x4 v = xr[ps] + *(const f32x4*)(tile + lr * EPS + wn * 64 + fr * 4);
;     *(f32x4*)(XF + (size_t)row * DM + col) = v;
.LBB0_225:
	s_or_b64 exec, exec, s[10:11]
	v_add_u32_e32 v6, 0x48, v70
	v_ashrrev_i32_e32 v7, 31, v6
	v_lshlrev_b64 v[8:9], 12, v[6:7]
	v_lshl_add_u64 v[8:9], v[66:67], 0, v[8:9]
	s_waitcnt lgkmcnt(6)
	v_pk_add_f32 v[4:5], v[40:41], v[218:219]
	v_pk_add_f32 v[2:3], v[38:39], v[216:217]
	s_mov_b64 s[10:11], -1
	s_and_b64 vcc, exec, s[38:39]
	global_store_dwordx4 v[8:9], v[2:5], off
	s_cbranch_vccnz .LBB0_227
	s_mov_b64 s[10:11], 0

; DI void phaseE_tile(const P& p, int layer, int mt, int nt, char* lds) {
;     ...
;   for (int ps = 0; ps < 16; ++ps) {
;     const int lr = ps * 8 + wm * 4 + fq, row = row0 + lr;
;     const f32x4 v = xr[ps] + *(const f32x4*)(tile + lr * EPS + wn * 64 + fr * 4);
;     *(f32x4*)(XF + (size_t)row * DM + col) = v;
.LBB0_231:
	s_or_b64 exec, exec, s[10:11]
	v_add_u32_e32 v6, 0x50, v70
	v_ashrrev_i32_e32 v7, 31, v6
	v_lshlrev_b64 v[8:9], 12, v[6:7]
	v_lshl_add_u64 v[8:9], v[66:67], 0, v[8:9]
	s_waitcnt lgkmcnt(5)
	v_pk_add_f32 v[4:5], v[44:45], v[222:223]
	v_pk_add_f32 v[2:3], v[42:43], v[220:221]
	s_mov_b64 s[10:11], -1
	s_and_b64 vcc, exec, s[38:39]
	global_store_dwordx4 v[8:9], v[2:5], off
	s_cbranch_vccnz .LBB0_233
	s_mov_b64 s[10:11], 0

; DI void phaseE_tile(const P& p, int layer, int mt, int nt, char* lds) {
;     ...
;   for (int ps = 0; ps < 16; ++ps) {
;     const int lr = ps * 8 + wm * 4 + fq, row = row0 + lr;
;     const f32x4 v = xr[ps] + *(const f32x4*)(tile + lr * EPS + wn * 64 + fr * 4);
;     *(f32x4*)(XF + (size_t)row * DM + col) = v;
.LBB0_237:
	s_or_b64 exec, exec, s[10:11]
	v_add_u32_e32 v6, 0x58, v70
	v_ashrrev_i32_e32 v7, 31, v6
	v_lshlrev_b64 v[8:9], 12, v[6:7]
	v_lshl_add_u64 v[8:9], v[66:67], 0, v[8:9]
	s_waitcnt lgkmcnt(4)
	v_pk_add_f32 v[4:5], v[48:49], v[226:227]
	v_pk_add_f32 v[2:3], v[46:47], v[224:225]
	s_mov_b64 s[10:11], -1
	s_and_b64 vcc, exec, s[38:39]
	global_store_dwordx4 v[8:9], v[2:5], off
	s_cbranch_vccnz .LBB0_239
	s_mov_b64 s[10:11], 0

; DI void phaseE_tile(const P& p, int layer, int mt, int nt, char* lds) {
;     ...
;   for (int ps = 0; ps < 16; ++ps) {
;     const int lr = ps * 8 + wm * 4 + fq, row = row0 + lr;
;     const f32x4 v = xr[ps] + *(const f32x4*)(tile + lr * EPS + wn * 64 + fr * 4);
;     *(f32x4*)(XF + (size_t)row * DM + col) = v;
.LBB0_243:
	s_or_b64 exec, exec, s[10:11]
	v_add_u32_e32 v6, 0x60, v70
	v_ashrrev_i32_e32 v7, 31, v6
	v_lshlrev_b64 v[8:9], 12, v[6:7]
	v_lshl_add_u64 v[8:9], v[66:67], 0, v[8:9]
	s_waitcnt lgkmcnt(3)
	v_pk_add_f32 v[4:5], v[52:53], v[230:231]
	v_pk_add_f32 v[2:3], v[50:51], v[228:229]
	s_mov_b64 s[10:11], -1
	s_and_b64 vcc, exec, s[38:39]
	global_store_dwordx4 v[8:9], v[2:5], off
	s_cbranch_vccnz .LBB0_245
	s_mov_b64 s[10:11], 0

; DI void phaseE_tile(const P& p, int layer, int mt, int nt, char* lds) {
;     ...
;   for (int ps = 0; ps < 16; ++ps) {
;     const int lr = ps * 8 + wm * 4 + fq, row = row0 + lr;
;     const f32x4 v = xr[ps] + *(const f32x4*)(tile + lr * EPS + wn * 64 + fr * 4);
;     *(f32x4*)(XF + (size_t)row * DM + col) = v;
.LBB0_249:
	s_or_b64 exec, exec, s[10:11]
	v_add_u32_e32 v6, 0x68, v70
	v_ashrrev_i32_e32 v7, 31, v6
	v_lshlrev_b64 v[8:9], 12, v[6:7]
	v_lshl_add_u64 v[8:9], v[66:67], 0, v[8:9]
	s_waitcnt lgkmcnt(2)
	v_pk_add_f32 v[4:5], v[56:57], v[234:235]
	v_pk_add_f32 v[2:3], v[54:55], v[232:233]
	s_mov_b64 s[10:11], -1
	s_and_b64 vcc, exec, s[38:39]
	global_store_dwordx4 v[8:9], v[2:5], off
	s_cbranch_vccnz .LBB0_251
	s_mov_b64 s[10:11], 0

; DI void phaseE_tile(const P& p, int layer, int mt, int nt, char* lds) {
;     ...
;   for (int ps = 0; ps < 16; ++ps) {
;     const int lr = ps * 8 + wm * 4 + fq, row = row0 + lr;
;     const f32x4 v = xr[ps] + *(const f32x4*)(tile + lr * EPS + wn * 64 + fr * 4);
;     *(f32x4*)(XF + (size_t)row * DM + col) = v;
.LBB0_255:
	s_or_b64 exec, exec, s[10:11]
	v_add_u32_e32 v6, 0x70, v70
	v_ashrrev_i32_e32 v7, 31, v6
	v_lshlrev_b64 v[8:9], 12, v[6:7]
	v_lshl_add_u64 v[8:9], v[66:67], 0, v[8:9]
	s_waitcnt lgkmcnt(1)
	v_pk_add_f32 v[4:5], v[60:61], v[152:153]
	v_pk_add_f32 v[2:3], v[58:59], v[150:151]
	s_mov_b64 s[10:11], -1
	s_and_b64 vcc, exec, s[38:39]
	global_store_dwordx4 v[8:9], v[2:5], off
	s_cbranch_vccnz .LBB0_257
	s_mov_b64 s[10:11], 0

; DI void phaseE_tile(const P& p, int layer, int mt, int nt, char* lds) {
;     ...
;   for (int ps = 0; ps < 16; ++ps) {
;     const int lr = ps * 8 + wm * 4 + fq, row = row0 + lr;
;     const f32x4 v = xr[ps] + *(const f32x4*)(tile + lr * EPS + wn * 64 + fr * 4);
;     *(f32x4*)(XF + (size_t)row * DM + col) = v;
.LBB0_261:
	s_or_b64 exec, exec, s[10:11]
	v_add_u32_e32 v6, 0x78, v70
	v_ashrrev_i32_e32 v7, 31, v6
	v_lshlrev_b64 v[8:9], 12, v[6:7]
	v_lshl_add_u64 v[8:9], v[66:67], 0, v[8:9]
	s_waitcnt lgkmcnt(0)
	v_pk_add_f32 v[4:5], v[64:65], v[156:157]
	v_pk_add_f32 v[2:3], v[62:63], v[154:155]
	s_and_b64 vcc, exec, s[38:39]
	s_mov_b64 s[10:11], -1
	global_store_dwordx4 v[8:9], v[2:5], off
	s_cbranch_vccnz .LBB0_263
	s_mov_b64 s[10:11], 0

; DI unsigned pk2(float lo, float hi) { unsigned r; asm("v_cvt_pk_bf16_f32 %0, %1, %2" : "=v"(r) : "v"(lo), "v"(hi)); return r; }
; DI void phaseD_tile(const P& p, int layer, int mt, int nt, char* lds) {
;     ...
;   bf16_t* MG = (bf16_t*)(p.ws + W_MERGED);
; #pragma unroll 1
;   for (int ps = 0; ps < 16; ++ps) {
;     const int lr = ps * 8 + wm * 4 + fq;
;     const f32x4 v = *(const f32x4*)(tile + lr * EPS + wn * 64 + fr * 4);
;     *(u32x2*)(MG + (size_t)(row0 + lr) * LDX + col0 + wn * 64 + fr * 4) = u32x2{pk2(v.x, v.y), pk2(v.z, v.w)};
;   }
;   __syncthreads();
.LBB0_278:
	ds_read_b128 v[6:9], v4
	ds_read_b128 v[10:13], v4 offset:4224
	ds_read_b128 v[14:17], v4 offset:8448
	ds_read_b128 v[18:21], v4 offset:12672
	ds_read_b128 v[22:25], v4 offset:16896
	ds_read_b128 v[26:29], v4 offset:21120
	ds_read_b128 v[30:33], v4 offset:25344
	ds_read_b128 v[34:37], v4 offset:29568
	ds_read_b128 v[38:41], v4 offset:33792
	ds_read_b128 v[42:45], v4 offset:38016
	ds_read_b128 v[46:49], v4 offset:42240
	ds_read_b128 v[50:53], v4 offset:46464
	ds_read_b128 v[54:57], v4 offset:50688
	ds_read_b128 v[58:61], v4 offset:54912
	ds_read_b128 v[62:65], v4 offset:59136
	ds_read_b128 v[66:69], v4 offset:63360
	s_waitcnt lgkmcnt(15)
	v_cvt_pk_bf16_f32 v6, v6, v7
	v_cvt_pk_bf16_f32 v7, v8, v9
	v_mad_i64_i32 v[70:71], s[6:7], v0, s5, v[2:3]
	v_add_u32_e32 v0, 8, v0
	global_store_dwordx2 v[70:71], v[6:7], off
	s_waitcnt lgkmcnt(14)
	v_cvt_pk_bf16_f32 v10, v10, v11
	v_cvt_pk_bf16_f32 v11, v12, v13
	v_mad_i64_i32 v[70:71], s[6:7], v0, s5, v[2:3]
	v_add_u32_e32 v0, 8, v0
	global_store_dwordx2 v[70:71], v[10:11], off
	s_waitcnt lgkmcnt(13)
	v_cvt_pk_bf16_f32 v14, v14, v15
	v_cvt_pk_bf16_f32 v15, v16, v17
	v_mad_i64_i32 v[70:71], s[6:7], v0, s5, v[2:3]
	v_add_u32_e32 v0, 8, v0
	global_store_dwordx2 v[70:71], v[14:15], off
	s_waitcnt lgkmcnt(12)
	v_cvt_pk_bf16_f32 v18, v18, v19
	v_cvt_pk_bf16_f32 v19, v20, v21
	v_mad_i64_i32 v[70:71], s[6:7], v0, s5, v[2:3]
	v_add_u32_e32 v0, 8, v0
	global_store_dwordx2 v[70:71], v[18:19], off
	s_waitcnt lgkmcnt(11)
	v_cvt_pk_bf16_f32 v22, v22, v23
	v_cvt_pk_bf16_f32 v23, v24, v25
	v_mad_i64_i32 v[70:71], s[6:7], v0, s5, v[2:3]
	v_add_u32_e32 v0, 8, v0
	global_store_dwordx2 v[70:71], v[22:23], off
	s_waitcnt lgkmcnt(10)
	v_cvt_pk_bf16_f32 v26, v26, v27
	v_cvt_pk_bf16_f32 v27, v28, v29
	v_mad_i64_i32 v[70:71], s[6:7], v0, s5, v[2:3]
	v_add_u32_e32 v0, 8, v0
	global_store_dwordx2 v[70:71], v[26:27], off
	s_waitcnt lgkmcnt(9)
	v_cvt_pk_bf16_f32 v30, v30, v31
	v_cvt_pk_bf16_f32 v31, v32, v33
	v_mad_i64_i32 v[70:71], s[6:7], v0, s5, v[2:3]
	v_add_u32_e32 v0, 8, v0
	global_store_dwordx2 v[70:71], v[30:31], off
	s_waitcnt lgkmcnt(8)
	v_cvt_pk_bf16_f32 v34, v34, v35
	v_cvt_pk_bf16_f32 v35, v36, v37
	v_mad_i64_i32 v[70:71], s[6:7], v0, s5, v[2:3]
	v_add_u32_e32 v0, 8, v0
	global_store_dwordx2 v[70:71], v[34:35], off
	s_waitcnt lgkmcnt(7)
	v_cvt_pk_bf16_f32 v38, v38, v39
	v_cvt_pk_bf16_f32 v39, v40, v41
	v_mad_i64_i32 v[70:71], s[6:7], v0, s5, v[2:3]
	v_add_u32_e32 v0, 8, v0
	global_store_dwordx2 v[70:71], v[38:39], off
	s_waitcnt lgkmcnt(6)
	v_cvt_pk_bf16_f32 v42, v42, v43
	v_cvt_pk_bf16_f32 v43, v44, v45
	v_mad_i64_i32 v[70:71], s[6:7], v0, s5, v[2:3]
	v_add_u32_e32 v0, 8, v0
	global_store_dwordx2 v[70:71], v[42:43], off
	s_waitcnt lgkmcnt(5)
	v_cvt_pk_bf16_f32 v46, v46, v47
	v_cvt_pk_bf16_f32 v47, v48, v49
	v_mad_i64_i32 v[70:71], s[6:7], v0, s5, v[2:3]
	v_add_u32_e32 v0, 8, v0
	global_store_dwordx2 v[70:71], v[46:47], off
	s_waitcnt lgkmcnt(4)
	v_cvt_pk_bf16_f32 v50, v50, v51
	v_cvt_pk_bf16_f32 v51, v52, v53
	v_mad_i64_i32 v[70:71], s[6:7], v0, s5, v[2:3]
	v_add_u32_e32 v0, 8, v0
	global_store_dwordx2 v[70:71], v[50:51], off
	s_waitcnt lgkmcnt(3)
	v_cvt_pk_bf16_f32 v54, v54, v55
	v_cvt_pk_bf16_f32 v55, v56, v57
	v_mad_i64_i32 v[70:71], s[6:7], v0, s5, v[2:3]
	v_add_u32_e32 v0, 8, v0
	global_store_dwordx2 v[70:71], v[54:55], off
	s_waitcnt lgkmcnt(2)
	v_cvt_pk_bf16_f32 v58, v58, v59
	v_cvt_pk_bf16_f32 v59, v60, v61
	v_mad_i64_i32 v[70:71], s[6:7], v0, s5, v[2:3]
	v_add_u32_e32 v0, 8, v0
	global_store_dwordx2 v[70:71], v[58:59], off
	s_waitcnt lgkmcnt(1)
	v_cvt_pk_bf16_f32 v62, v62, v63
	v_cvt_pk_bf16_f32 v63, v64, v65
	v_mad_i64_i32 v[70:71], s[6:7], v0, s5, v[2:3]
	v_add_u32_e32 v0, 8, v0
	global_store_dwordx2 v[70:71], v[62:63], off
	s_waitcnt lgkmcnt(0)
	v_cvt_pk_bf16_f32 v66, v66, v67
	v_cvt_pk_bf16_f32 v67, v68, v69
	v_mad_i64_i32 v[70:71], s[6:7], v0, s5, v[2:3]
	v_add_u32_e32 v0, 8, v0
	global_store_dwordx2 v[70:71], v[66:67], off
	s_add_i32 s17, s17, s52
	s_cmp_ge_i32 s17, s16
	s_mov_b64 s[60:61], 0x20000
	s_movk_i32 s69, 0x1040
	s_movk_i32 s64, 0x54a0
	s_brev_b32 s65, 1
	s_mov_b32 s68, s72
	s_barrier
	s_cbranch_scc0 .LBB0_273
